# P0a weight-transpose loops unrolled x2 so 32 global loads are in flight per wave (was 16, vmcnt(0) between)
# speedup vs baseline: 1.0060x; 1.0044x over previous
; #define LAS __attribute__((address_space(3)))
; #define LAS __attribute__((address_space(3)))
; __device__ __forceinline__ void transpose_item(const float* W, int K, int N, bf16_t* WT, int k0, int n_src, int n_dst, LAS float* scr, int lane) {
; #pragma unroll 8
;     for (int i = 0; i < 32; ++i) { const int kk = 2 * i + (lane >> 5); scr[kk * 33 + (lane & 31)] = W[(size_t)(k0 + kk) * N + n_src + (lane & 31)]; }
; __device__ __forceinline__ void convert_layer(const Params& p, LAS unsigned char* lds, int l, int gwi, int ngw, int lane, int wid) {
;     ...
;         { const int kb = rr / 32, nb = rr % 32; transpose_item(p.w_ffn_out + (size_t)l * FFH * DM, FFH, DM, (bf16_t*)(wl + W_FO), 64 * kb, 32 * nb, 32 * nb, scr, lane); }
.LBB0_34:
	s_lshl_b32 s44, s22, 1
	s_lshl_b32 s45, s23, 1
	v_or_b32_e32 v4, s44, v1
	v_or_b32_e32 v35, s45, v2
	s_add_i32 s46, s44, 4
	s_add_i32 s47, s45, 4
	s_add_i32 s48, s44, 8
	s_add_i32 s49, s45, 8
	s_add_i32 s50, s44, 12
	s_add_i32 s51, s45, 12
	s_add_i32 s52, s44, 16
	s_add_i32 s53, s45, 16
	s_add_i32 s54, s44, 20
	s_add_i32 s55, s45, 20
	s_add_i32 s56, s44, 24
	s_add_i32 s57, s45, 24
	s_add_i32 s44, s44, 28
	s_add_i32 s45, s45, 28
	v_add_u32_e32 v50, v35, v34
	v_or_b32_e32 v47, s46, v1
	v_or_b32_e32 v80, s47, v2
	v_or_b32_e32 v81, s48, v1
	v_or_b32_e32 v82, s49, v2
	v_or_b32_e32 v83, s50, v1
	v_or_b32_e32 v84, s51, v2
	v_or_b32_e32 v85, s52, v1
	v_or_b32_e32 v86, s53, v2
	v_or_b32_e32 v87, s54, v1
	v_or_b32_e32 v88, s55, v2
	v_or_b32_e32 v89, s56, v1
	v_or_b32_e32 v90, s57, v2
	v_or_b32_e32 v91, s44, v1
	v_or_b32_e32 v92, s45, v2
	v_add_u32_e32 v48, v4, v3
	v_ashrrev_i32_e32 v51, 31, v50
	v_add_u32_e32 v52, v47, v3
	v_add_u32_e32 v54, v80, v34
	v_add_u32_e32 v56, v81, v3
	v_add_u32_e32 v58, v82, v34
	v_add_u32_e32 v60, v83, v3
	v_add_u32_e32 v62, v84, v34
	v_add_u32_e32 v64, v85, v3
	v_add_u32_e32 v66, v86, v34
	v_add_u32_e32 v68, v87, v3
	v_add_u32_e32 v70, v88, v34
	v_add_u32_e32 v72, v89, v3
	v_add_u32_e32 v74, v90, v34
	v_add_u32_e32 v76, v91, v3
	v_add_u32_e32 v78, v92, v34
	v_ashrrev_i32_e32 v49, 31, v48
	v_lshlrev_b64 v[50:51], 12, v[50:51]
	v_ashrrev_i32_e32 v55, 31, v54
	v_ashrrev_i32_e32 v53, 31, v52
	v_ashrrev_i32_e32 v59, 31, v58
	v_ashrrev_i32_e32 v57, 31, v56
	v_ashrrev_i32_e32 v63, 31, v62
	v_ashrrev_i32_e32 v61, 31, v60
	v_ashrrev_i32_e32 v67, 31, v66
	v_ashrrev_i32_e32 v65, 31, v64
	v_ashrrev_i32_e32 v71, 31, v70
	v_ashrrev_i32_e32 v69, 31, v68
	v_ashrrev_i32_e32 v75, 31, v74
	v_ashrrev_i32_e32 v73, 31, v72
	v_ashrrev_i32_e32 v79, 31, v78
	v_ashrrev_i32_e32 v77, 31, v76
	v_lshlrev_b64 v[48:49], 12, v[48:49]
	v_lshl_add_u64 v[50:51], v[36:37], 0, v[50:51]
	v_lshlrev_b64 v[52:53], 12, v[52:53]
	v_lshlrev_b64 v[54:55], 12, v[54:55]
	v_lshlrev_b64 v[56:57], 12, v[56:57]
	v_lshlrev_b64 v[58:59], 12, v[58:59]
	v_lshlrev_b64 v[60:61], 12, v[60:61]
	v_lshlrev_b64 v[62:63], 12, v[62:63]
	v_lshlrev_b64 v[64:65], 12, v[64:65]
	v_lshlrev_b64 v[66:67], 12, v[66:67]
	v_lshlrev_b64 v[68:69], 12, v[68:69]
	v_lshlrev_b64 v[70:71], 12, v[70:71]
	v_lshlrev_b64 v[72:73], 12, v[72:73]
	v_lshlrev_b64 v[74:75], 12, v[74:75]
	v_lshlrev_b64 v[76:77], 12, v[76:77]
	v_lshlrev_b64 v[78:79], 12, v[78:79]
	v_lshl_add_u64 v[48:49], v[36:37], 0, v[48:49]
	v_lshl_add_u64 v[54:55], v[36:37], 0, v[54:55]
	v_lshl_add_u64 v[52:53], v[36:37], 0, v[52:53]
	v_lshl_add_u64 v[58:59], v[36:37], 0, v[58:59]
	v_lshl_add_u64 v[56:57], v[36:37], 0, v[56:57]
	v_lshl_add_u64 v[62:63], v[36:37], 0, v[62:63]
	v_lshl_add_u64 v[60:61], v[36:37], 0, v[60:61]
	v_lshl_add_u64 v[66:67], v[36:37], 0, v[66:67]
	v_lshl_add_u64 v[64:65], v[36:37], 0, v[64:65]
	v_lshl_add_u64 v[70:71], v[36:37], 0, v[70:71]
	v_lshl_add_u64 v[68:69], v[36:37], 0, v[68:69]
	v_lshl_add_u64 v[74:75], v[36:37], 0, v[74:75]
	v_lshl_add_u64 v[72:73], v[36:37], 0, v[72:73]
	v_lshl_add_u64 v[78:79], v[36:37], 0, v[78:79]
	v_lshl_add_u64 v[76:77], v[36:37], 0, v[76:77]
	global_load_dword v93, v[50:51], off
	global_load_dword v94, v[48:49], off
	global_load_dword v95, v[54:55], off
	global_load_dword v96, v[52:53], off
	global_load_dword v97, v[58:59], off
	global_load_dword v98, v[56:57], off
	global_load_dword v99, v[62:63], off
	global_load_dword v100, v[60:61], off
	global_load_dword v101, v[66:67], off
	global_load_dword v102, v[64:65], off
	global_load_dword v103, v[70:71], off
	global_load_dword v104, v[68:69], off
	global_load_dword v105, v[74:75], off
	global_load_dword v106, v[72:73], off
	global_load_dword v107, v[78:79], off
	global_load_dword v108, v[76:77], off
	s_add_i32 s23, s23, 16
	s_add_i32 s22, s22, 16
	s_add_i32 s43, s43, -16
	s_cmp_lg_u32 s43, 0
	s_lshl_b32 s44, s22, 1
	s_lshl_b32 s45, s23, 1
	v_or_b32_e32 v174, s44, v1
	v_or_b32_e32 v175, s45, v2
	s_add_i32 s46, s44, 4
	s_add_i32 s47, s45, 4
	s_add_i32 s48, s44, 8
	s_add_i32 s49, s45, 8
	s_add_i32 s50, s44, 12
	s_add_i32 s51, s45, 12
	s_add_i32 s52, s44, 16
	s_add_i32 s53, s45, 16
	s_add_i32 s54, s44, 20
	s_add_i32 s55, s45, 20
	s_add_i32 s56, s44, 24
	s_add_i32 s57, s45, 24
	s_add_i32 s44, s44, 28
	s_add_i32 s45, s45, 28
	v_add_u32_e32 v114, v175, v34
	v_or_b32_e32 v111, s46, v1
	v_or_b32_e32 v144, s47, v2
	v_or_b32_e32 v145, s48, v1
	v_or_b32_e32 v146, s49, v2
	v_or_b32_e32 v147, s50, v1
	v_or_b32_e32 v148, s51, v2
	v_or_b32_e32 v149, s52, v1
	v_or_b32_e32 v150, s53, v2
	v_or_b32_e32 v151, s54, v1
	v_or_b32_e32 v152, s55, v2
	v_or_b32_e32 v153, s56, v1
	v_or_b32_e32 v154, s57, v2
	v_or_b32_e32 v155, s44, v1
	v_or_b32_e32 v156, s45, v2
	v_add_u32_e32 v112, v174, v3
	v_ashrrev_i32_e32 v115, 31, v114
	v_add_u32_e32 v116, v111, v3
	v_add_u32_e32 v118, v144, v34
	v_add_u32_e32 v120, v145, v3
	v_add_u32_e32 v122, v146, v34
	v_add_u32_e32 v124, v147, v3
	v_add_u32_e32 v126, v148, v34
	v_add_u32_e32 v128, v149, v3
	v_add_u32_e32 v130, v150, v34
	v_add_u32_e32 v132, v151, v3
	v_add_u32_e32 v134, v152, v34
	v_add_u32_e32 v136, v153, v3
	v_add_u32_e32 v138, v154, v34
	v_add_u32_e32 v140, v155, v3
	v_add_u32_e32 v142, v156, v34
	v_ashrrev_i32_e32 v113, 31, v112
	v_lshlrev_b64 v[114:115], 12, v[114:115]
	v_ashrrev_i32_e32 v119, 31, v118
	v_ashrrev_i32_e32 v117, 31, v116
	v_ashrrev_i32_e32 v123, 31, v122
	v_ashrrev_i32_e32 v121, 31, v120
	v_ashrrev_i32_e32 v127, 31, v126
	v_ashrrev_i32_e32 v125, 31, v124
	v_ashrrev_i32_e32 v131, 31, v130
	v_ashrrev_i32_e32 v129, 31, v128
	v_ashrrev_i32_e32 v135, 31, v134
	v_ashrrev_i32_e32 v133, 31, v132
; __device__ __forceinline__ void transpose_item(const float* W, int K, int N, bf16_t* WT, int k0, int n_src, int n_dst, LAS float* scr, int lane) {
;     ...
;     for (int i = 0; i < 32; ++i) { const int kk = 2 * i + (lane >> 5); scr[kk * 33 + (lane & 31)] = W[(size_t)(k0 + kk) * N + n_src + (lane & 31)]; }
	v_ashrrev_i32_e32 v139, 31, v138
	v_ashrrev_i32_e32 v137, 31, v136
	v_ashrrev_i32_e32 v143, 31, v142
	v_ashrrev_i32_e32 v141, 31, v140
	v_lshlrev_b64 v[112:113], 12, v[112:113]
	v_lshl_add_u64 v[114:115], v[36:37], 0, v[114:115]
	v_lshlrev_b64 v[116:117], 12, v[116:117]
	v_lshlrev_b64 v[118:119], 12, v[118:119]
	v_lshlrev_b64 v[120:121], 12, v[120:121]
	v_lshlrev_b64 v[122:123], 12, v[122:123]
	v_lshlrev_b64 v[124:125], 12, v[124:125]
	v_lshlrev_b64 v[126:127], 12, v[126:127]
	v_lshlrev_b64 v[128:129], 12, v[128:129]
	v_lshlrev_b64 v[130:131], 12, v[130:131]
	v_lshlrev_b64 v[132:133], 12, v[132:133]
	v_lshlrev_b64 v[134:135], 12, v[134:135]
	v_lshlrev_b64 v[136:137], 12, v[136:137]
	v_lshlrev_b64 v[138:139], 12, v[138:139]
	v_lshlrev_b64 v[140:141], 12, v[140:141]
	v_lshlrev_b64 v[142:143], 12, v[142:143]
	v_lshl_add_u64 v[112:113], v[36:37], 0, v[112:113]
	v_lshl_add_u64 v[118:119], v[36:37], 0, v[118:119]
	v_lshl_add_u64 v[116:117], v[36:37], 0, v[116:117]
	v_lshl_add_u64 v[122:123], v[36:37], 0, v[122:123]
	v_lshl_add_u64 v[120:121], v[36:37], 0, v[120:121]
	v_lshl_add_u64 v[126:127], v[36:37], 0, v[126:127]
	v_lshl_add_u64 v[124:125], v[36:37], 0, v[124:125]
	v_lshl_add_u64 v[130:131], v[36:37], 0, v[130:131]
	v_lshl_add_u64 v[128:129], v[36:37], 0, v[128:129]
	v_lshl_add_u64 v[134:135], v[36:37], 0, v[134:135]
	v_lshl_add_u64 v[132:133], v[36:37], 0, v[132:133]
	v_lshl_add_u64 v[138:139], v[36:37], 0, v[138:139]
	v_lshl_add_u64 v[136:137], v[36:37], 0, v[136:137]
	v_lshl_add_u64 v[142:143], v[36:37], 0, v[142:143]
	v_lshl_add_u64 v[140:141], v[36:37], 0, v[140:141]
	global_load_dword v157, v[114:115], off
	global_load_dword v158, v[112:113], off
	global_load_dword v159, v[118:119], off
	global_load_dword v160, v[116:117], off
	global_load_dword v161, v[122:123], off
	global_load_dword v162, v[120:121], off
	global_load_dword v163, v[126:127], off
	global_load_dword v164, v[124:125], off
	global_load_dword v165, v[130:131], off
	global_load_dword v166, v[128:129], off
	global_load_dword v167, v[134:135], off
	global_load_dword v168, v[132:133], off
	global_load_dword v169, v[138:139], off
	global_load_dword v170, v[136:137], off
	global_load_dword v171, v[142:143], off
	global_load_dword v172, v[140:141], off
	s_add_i32 s23, s23, 16
	s_add_i32 s22, s22, 16
	s_add_i32 s43, s43, -16
	s_cmp_lg_u32 s43, 0
	v_mad_u64_u32 v[48:49], s[44:45], v35, s24, v[6:7]
	v_mad_u64_u32 v[50:51], s[44:45], v4, s24, v[6:7]
	v_mad_u64_u32 v[52:53], s[44:45], v80, s24, v[6:7]
	v_mad_u64_u32 v[54:55], s[44:45], v47, s24, v[6:7]
	v_mad_u64_u32 v[56:57], s[44:45], v82, s24, v[6:7]
	v_mad_u64_u32 v[58:59], s[44:45], v81, s24, v[6:7]
	v_mad_u64_u32 v[60:61], s[44:45], v84, s24, v[6:7]
	v_mad_u64_u32 v[62:63], s[44:45], v83, s24, v[6:7]
	v_mad_u64_u32 v[64:65], s[44:45], v86, s24, v[6:7]
	v_mad_u64_u32 v[66:67], s[44:45], v85, s24, v[6:7]
	v_mad_u64_u32 v[68:69], s[44:45], v88, s24, v[6:7]
	v_mad_u64_u32 v[70:71], s[44:45], v87, s24, v[6:7]
	v_mad_u64_u32 v[72:73], s[44:45], v90, s24, v[6:7]
	v_mad_u64_u32 v[74:75], s[44:45], v89, s24, v[6:7]
	v_mad_u64_u32 v[76:77], s[44:45], v92, s24, v[6:7]
	v_mad_u64_u32 v[78:79], s[44:45], v91, s24, v[6:7]
	s_waitcnt vmcnt(16)
; #define LAS __attribute__((address_space(3)))
; #define LAS __attribute__((address_space(3)))
; __device__ __forceinline__ unsigned pkbf(float lo, float hi) { return pg8::cvt_pk_bf16(lo, hi); }
; __device__ __forceinline__ void transpose_item(const float* W, int K, int N, bf16_t* WT, int k0, int n_src, int n_dst, LAS float* scr, int lane) {
;     ...
;     for (int i = 0; i < 32; ++i) { const int kk = 2 * i + (lane >> 5); scr[kk * 33 + (lane & 31)] = W[(size_t)(k0 + kk) * N + n_src + (lane & 31)]; }
;     asm volatile("s_waitcnt lgkmcnt(0)" ::: "memory");
;     const int c = lane & 7;
; #pragma unroll
;     for (int j = 0; j < 4; ++j) {
;         const int n = (lane >> 3) + 8 * j; const LAS float* s = scr + (8 * c) * 33 + n;
;         u32x4 o; o.x = pkbf(s[0 * 33], s[1 * 33]); o.y = pkbf(s[2 * 33], s[3 * 33]); o.z = pkbf(s[4 * 33], s[5 * 33]); o.w = pkbf(s[6 * 33], s[7 * 33]);
;         *(u32x4*)(WT + (size_t)(n_dst + n) * K + k0 + 8 * c) = o;
;     }
	ds_write_b32 v48, v93
	ds_write_b32 v50, v94
	ds_write_b32 v52, v95
	ds_write_b32 v54, v96
	ds_write_b32 v56, v97
	ds_write_b32 v58, v98
	ds_write_b32 v60, v99
	ds_write_b32 v62, v100
	ds_write_b32 v64, v101
	ds_write_b32 v66, v102
	ds_write_b32 v68, v103
	ds_write_b32 v70, v104
	ds_write_b32 v72, v105
	ds_write_b32 v74, v106
	ds_write_b32 v76, v107
	ds_write_b32 v78, v108
	v_mad_u64_u32 v[112:113], s[44:45], v175, s24, v[6:7]
	v_mad_u64_u32 v[114:115], s[44:45], v174, s24, v[6:7]
	v_mad_u64_u32 v[116:117], s[44:45], v144, s24, v[6:7]
	v_mad_u64_u32 v[118:119], s[44:45], v111, s24, v[6:7]
	v_mad_u64_u32 v[120:121], s[44:45], v146, s24, v[6:7]
	v_mad_u64_u32 v[122:123], s[44:45], v145, s24, v[6:7]
	v_mad_u64_u32 v[124:125], s[44:45], v148, s24, v[6:7]
	v_mad_u64_u32 v[126:127], s[44:45], v147, s24, v[6:7]
	v_mad_u64_u32 v[128:129], s[44:45], v150, s24, v[6:7]
	v_mad_u64_u32 v[130:131], s[44:45], v149, s24, v[6:7]
	v_mad_u64_u32 v[132:133], s[44:45], v152, s24, v[6:7]
	v_mad_u64_u32 v[134:135], s[44:45], v151, s24, v[6:7]
	v_mad_u64_u32 v[136:137], s[44:45], v154, s24, v[6:7]
	v_mad_u64_u32 v[138:139], s[44:45], v153, s24, v[6:7]
	v_mad_u64_u32 v[140:141], s[44:45], v156, s24, v[6:7]
	v_mad_u64_u32 v[142:143], s[44:45], v155, s24, v[6:7]
	s_waitcnt vmcnt(0)
	ds_write_b32 v112, v157
	ds_write_b32 v114, v158
	ds_write_b32 v116, v159
	ds_write_b32 v118, v160
	ds_write_b32 v120, v161
	ds_write_b32 v122, v162
	ds_write_b32 v124, v163
	ds_write_b32 v126, v164
	ds_write_b32 v128, v165
	ds_write_b32 v130, v166
	ds_write_b32 v132, v167
	ds_write_b32 v134, v168
	ds_write_b32 v136, v169
	ds_write_b32 v138, v170
	ds_write_b32 v140, v171
	ds_write_b32 v142, v172
	s_waitcnt lgkmcnt(0)
	ds_read2_b32 v[36:37], v38 offset1:33
	s_waitcnt lgkmcnt(0)
	v_cvt_pk_bf16_f32 v48, v36, v37
	ds_read2_b32 v[36:37], v38 offset0:66 offset1:99
	v_or_b32_e32 v3, v46, v7
	s_waitcnt lgkmcnt(0)
	v_cvt_pk_bf16_f32 v49, v36, v37
	ds_read2_b32 v[36:37], v38 offset0:132 offset1:165
	v_mov_b32_e32 v35, v5
	v_mul_u32_u24_e32 v3, 0xb00, v3
	s_waitcnt lgkmcnt(0)
	v_cvt_pk_bf16_f32 v50, v36, v37
	ds_read2_b32 v[36:37], v38 offset0:198 offset1:231
	v_lshl_add_u64 v[52:53], v[34:35], 1, v[20:21]
	v_lshlrev_b32_e32 v4, 1, v3
	s_waitcnt lgkmcnt(0)
	v_cvt_pk_bf16_f32 v51, v36, v37
	ds_read2_b32 v[34:35], v38 offset0:8 offset1:41
	v_lshl_add_u64 v[36:37], v[52:53], 0, v[4:5]
	v_or_b32_e32 v3, v46, v39
	global_store_dwordx4 v[36:37], v[48:51], off
	s_waitcnt lgkmcnt(0)
	v_cvt_pk_bf16_f32 v34, v34, v35
	ds_read2_b32 v[36:37], v38 offset0:74 offset1:107
	v_mul_u32_u24_e32 v3, 0xb00, v3
	s_waitcnt lgkmcnt(0)
	v_cvt_pk_bf16_f32 v35, v36, v37
	ds_read2_b32 v[36:37], v38 offset0:140 offset1:173
	v_lshlrev_b32_e32 v4, 1, v3
	s_waitcnt lgkmcnt(0)
	v_cvt_pk_bf16_f32 v36, v36, v37
	ds_read2_b32 v[48:49], v38 offset0:206 offset1:239
	s_waitcnt lgkmcnt(0)
	v_cvt_pk_bf16_f32 v37, v48, v49
	v_lshl_add_u64 v[50:51], v[52:53], 0, v[4:5]
	v_or_b32_e32 v3, v46, v40
	ds_read2_b32 v[48:49], v38 offset0:16 offset1:49
	global_store_dwordx4 v[50:51], v[34:37], off
	v_mul_u32_u24_e32 v3, 0xb00, v3
	v_lshlrev_b32_e32 v4, 1, v3
	s_waitcnt lgkmcnt(0)
	v_cvt_pk_bf16_f32 v34, v48, v49
	ds_read2_b32 v[36:37], v38 offset0:82 offset1:115
	s_waitcnt lgkmcnt(0)
	v_cvt_pk_bf16_f32 v35, v36, v37
	ds_read2_b32 v[36:37], v38 offset0:148 offset1:181
	v_or_b32_e32 v3, v46, v41
	s_waitcnt lgkmcnt(0)
	v_cvt_pk_bf16_f32 v36, v36, v37
	ds_read2_b32 v[48:49], v38 offset0:214 offset1:247
	s_waitcnt lgkmcnt(0)
	v_cvt_pk_bf16_f32 v37, v48, v49
	v_lshl_add_u64 v[50:51], v[52:53], 0, v[4:5]
	v_mul_u32_u24_e32 v3, 0xb00, v3
	ds_read2_b32 v[48:49], v38 offset0:24 offset1:57
	global_store_dwordx4 v[50:51], v[34:37], off
	v_lshlrev_b32_e32 v4, 1, v3
	v_lshl_add_u64 v[46:47], v[52:53], 0, v[4:5]
	s_waitcnt lgkmcnt(0)
	v_cvt_pk_bf16_f32 v34, v48, v49
	ds_read2_b32 v[36:37], v38 offset0:90 offset1:123
	s_waitcnt lgkmcnt(0)
	v_cvt_pk_bf16_f32 v35, v36, v37
	ds_read2_b32 v[36:37], v38 offset0:156 offset1:189
	s_waitcnt lgkmcnt(0)
	v_cvt_pk_bf16_f32 v36, v36, v37
	ds_read2_b32 v[48:49], v38 offset0:222 offset1:255
	s_waitcnt lgkmcnt(0)
	v_cvt_pk_bf16_f32 v37, v48, v49
	global_store_dwordx4 v[46:47], v[34:37], off
	s_waitcnt lgkmcnt(0)

; __device__ __forceinline__ int perm_fi(int cn) { const int pn = cn >> 8, pos = cn & 255; return (pos < 128) ? (128 * pn + pos) : (FFH + 128 * pn + pos - 128); }
; __device__ __forceinline__ void transpose_item(const float* W, int K, int N, bf16_t* WT, int k0, int n_src, int n_dst, LAS float* scr, int lane) {
;     ...
;     for (int i = 0; i < 32; ++i) { const int kk = 2 * i + (lane >> 5); scr[kk * 33 + (lane & 31)] = W[(size_t)(k0 + kk) * N + n_src + (lane & 31)]; }
; __device__ __forceinline__ void convert_layer(const Params& p, LAS unsigned char* lds, int l, int gwi, int ngw, int lane, int wid) {
;     ...
;         if (rr < 1152) { const int kb = rr / 72, nb = rr % 72; transpose_item(p.w_in + (size_t)l * DM * INW, DM, INW, (bf16_t*)(wl + W_IN), 64 * kb, perm_in(32 * nb), 32 * nb, scr, lane); continue; } rr -= 1152;
;         if (rr < 512) { const int kb = rr / 32, nb = rr % 32; transpose_item(p.w_out + (size_t)l * DM * DM, DM, DM, (bf16_t*)(wl + W_OUT), 64 * kb, 32 * nb, 32 * nb, scr, lane); continue; } rr -= 512;
;         if (rr < 2816) { const int kb = rr / 176, nb = rr % 176; transpose_item(p.w_ffn_in + (size_t)l * DM * FFI, DM, FFI, (bf16_t*)(wl + W_FI), 64 * kb, perm_fi(32 * nb), 32 * nb, scr, lane); continue; } rr -= 2816;
.LBB0_38:
	s_lshl_b32 s44, s43, 1
	s_lshl_b32 s45, s0, 1
	v_or_b32_e32 v4, s44, v1
	v_or_b32_e32 v78, s45, v2
	s_add_i32 s46, s44, 4
	s_add_i32 s47, s45, 4
	s_add_i32 s48, s44, 8
	s_add_i32 s49, s45, 8
	s_add_i32 s50, s44, 12
	s_add_i32 s51, s45, 12
	s_add_i32 s52, s44, 16
	s_add_i32 s53, s45, 16
	s_add_i32 s54, s44, 20
	s_add_i32 s55, s45, 20
	s_add_i32 s56, s44, 24
	s_add_i32 s57, s45, 24
	s_add_i32 s44, s44, 28
	s_add_i32 s45, s45, 28
	v_add_u32_e32 v46, v78, v34
	v_or_b32_e32 v79, s46, v1
	v_or_b32_e32 v80, s47, v2
	v_or_b32_e32 v81, s48, v1
	v_or_b32_e32 v82, s49, v2
	v_or_b32_e32 v83, s50, v1
	v_or_b32_e32 v84, s51, v2
	v_or_b32_e32 v85, s52, v1
	v_or_b32_e32 v86, s53, v2
	v_or_b32_e32 v87, s54, v1
	v_or_b32_e32 v88, s55, v2
	v_or_b32_e32 v89, s56, v1
	v_or_b32_e32 v90, s57, v2
	v_or_b32_e32 v91, s44, v1
	v_or_b32_e32 v92, s45, v2
	v_add_u32_e32 v48, v4, v3
	v_mad_u64_u32 v[46:47], s[44:45], v46, s34, v[36:37]
	v_add_u32_e32 v52, v79, v3
	v_add_u32_e32 v50, v80, v34
	v_add_u32_e32 v56, v81, v3
	v_add_u32_e32 v54, v82, v34
	v_add_u32_e32 v60, v83, v3
	v_add_u32_e32 v58, v84, v34
	v_add_u32_e32 v64, v85, v3
	v_add_u32_e32 v62, v86, v34
	v_add_u32_e32 v68, v87, v3
	v_add_u32_e32 v66, v88, v34
	v_add_u32_e32 v72, v89, v3
	v_add_u32_e32 v70, v90, v34
	v_add_u32_e32 v76, v91, v3
	v_add_u32_e32 v74, v92, v34
	v_mad_u64_u32 v[48:49], s[44:45], v48, s34, v[36:37]
	v_mad_u64_u32 v[50:51], s[44:45], v50, s34, v[36:37]
	v_mad_u64_u32 v[52:53], s[44:45], v52, s34, v[36:37]
	v_mad_u64_u32 v[54:55], s[44:45], v54, s34, v[36:37]
	v_mad_u64_u32 v[56:57], s[44:45], v56, s34, v[36:37]
	v_mad_u64_u32 v[58:59], s[44:45], v58, s34, v[36:37]
	v_mad_u64_u32 v[60:61], s[44:45], v60, s34, v[36:37]
	v_mad_u64_u32 v[62:63], s[44:45], v62, s34, v[36:37]
	v_mad_u64_u32 v[64:65], s[44:45], v64, s34, v[36:37]
	v_mad_u64_u32 v[66:67], s[44:45], v66, s34, v[36:37]
	v_mad_u64_u32 v[68:69], s[44:45], v68, s34, v[36:37]
	v_mad_u64_u32 v[70:71], s[44:45], v70, s34, v[36:37]
	v_mad_u64_u32 v[72:73], s[44:45], v72, s34, v[36:37]
	v_mad_u64_u32 v[74:75], s[44:45], v74, s34, v[36:37]
	v_mad_u64_u32 v[76:77], s[44:45], v76, s34, v[36:37]
	global_load_dword v93, v[46:47], off
	global_load_dword v94, v[48:49], off
	global_load_dword v95, v[50:51], off
	global_load_dword v96, v[52:53], off
	global_load_dword v97, v[54:55], off
	global_load_dword v98, v[56:57], off
	global_load_dword v99, v[58:59], off
	global_load_dword v100, v[60:61], off
	global_load_dword v101, v[62:63], off
	global_load_dword v102, v[64:65], off
	global_load_dword v103, v[66:67], off
	global_load_dword v104, v[68:69], off
	global_load_dword v105, v[70:71], off
	global_load_dword v106, v[72:73], off
	global_load_dword v107, v[74:75], off
	global_load_dword v108, v[76:77], off
	s_add_i32 s0, s0, 16
	s_add_i32 s43, s43, 16
	s_add_i32 s1, s1, -16
	s_cmp_lg_u32 s1, 0
	s_lshl_b32 s44, s43, 1
	s_lshl_b32 s45, s0, 1
	v_or_b32_e32 v174, s44, v1
	v_or_b32_e32 v142, s45, v2
	s_add_i32 s46, s44, 4
	s_add_i32 s47, s45, 4
	s_add_i32 s48, s44, 8
	s_add_i32 s49, s45, 8
	s_add_i32 s50, s44, 12
	s_add_i32 s51, s45, 12
	s_add_i32 s52, s44, 16
	s_add_i32 s53, s45, 16
	s_add_i32 s54, s44, 20
	s_add_i32 s55, s45, 20
	s_add_i32 s56, s44, 24
	s_add_i32 s57, s45, 24
	s_add_i32 s44, s44, 28
	s_add_i32 s45, s45, 28
	v_add_u32_e32 v110, v142, v34
	v_or_b32_e32 v143, s46, v1
	v_or_b32_e32 v144, s47, v2
	v_or_b32_e32 v145, s48, v1
	v_or_b32_e32 v146, s49, v2
	v_or_b32_e32 v147, s50, v1
	v_or_b32_e32 v148, s51, v2
	v_or_b32_e32 v149, s52, v1
	v_or_b32_e32 v150, s53, v2
	v_or_b32_e32 v151, s54, v1
	v_or_b32_e32 v152, s55, v2
	v_or_b32_e32 v153, s56, v1
	v_or_b32_e32 v154, s57, v2
	v_or_b32_e32 v155, s44, v1
	v_or_b32_e32 v156, s45, v2
	v_add_u32_e32 v112, v174, v3
	v_mad_u64_u32 v[110:111], s[44:45], v110, s34, v[36:37]
	v_add_u32_e32 v116, v143, v3
	v_add_u32_e32 v114, v144, v34
	v_add_u32_e32 v120, v145, v3
	v_add_u32_e32 v118, v146, v34
	v_add_u32_e32 v124, v147, v3
	v_add_u32_e32 v122, v148, v34
	v_add_u32_e32 v128, v149, v3
	v_add_u32_e32 v126, v150, v34
	v_add_u32_e32 v132, v151, v3
	v_add_u32_e32 v130, v152, v34
	v_add_u32_e32 v136, v153, v3
	v_add_u32_e32 v134, v154, v34
	v_add_u32_e32 v140, v155, v3
	v_add_u32_e32 v138, v156, v34
	v_mad_u64_u32 v[112:113], s[44:45], v112, s34, v[36:37]
	v_mad_u64_u32 v[114:115], s[44:45], v114, s34, v[36:37]
	v_mad_u64_u32 v[116:117], s[44:45], v116, s34, v[36:37]
	v_mad_u64_u32 v[118:119], s[44:45], v118, s34, v[36:37]
	v_mad_u64_u32 v[120:121], s[44:45], v120, s34, v[36:37]
	v_mad_u64_u32 v[122:123], s[44:45], v122, s34, v[36:37]
	v_mad_u64_u32 v[124:125], s[44:45], v124, s34, v[36:37]
	v_mad_u64_u32 v[126:127], s[44:45], v126, s34, v[36:37]
	v_mad_u64_u32 v[128:129], s[44:45], v128, s34, v[36:37]
	v_mad_u64_u32 v[130:131], s[44:45], v130, s34, v[36:37]
	v_mad_u64_u32 v[132:133], s[44:45], v132, s34, v[36:37]
	v_mad_u64_u32 v[134:135], s[44:45], v134, s34, v[36:37]
	v_mad_u64_u32 v[136:137], s[44:45], v136, s34, v[36:37]
	v_mad_u64_u32 v[138:139], s[44:45], v138, s34, v[36:37]
	v_mad_u64_u32 v[140:141], s[44:45], v140, s34, v[36:37]
	global_load_dword v157, v[110:111], off
	global_load_dword v158, v[112:113], off
	global_load_dword v159, v[114:115], off
	global_load_dword v160, v[116:117], off
	global_load_dword v161, v[118:119], off
	global_load_dword v162, v[120:121], off
	global_load_dword v163, v[122:123], off
	global_load_dword v164, v[124:125], off
	global_load_dword v165, v[126:127], off
	global_load_dword v166, v[128:129], off
	global_load_dword v167, v[130:131], off
	global_load_dword v168, v[132:133], off
	global_load_dword v169, v[134:135], off
	global_load_dword v170, v[136:137], off
	global_load_dword v171, v[138:139], off
	global_load_dword v172, v[140:141], off
	s_add_i32 s0, s0, 16
	s_add_i32 s43, s43, 16
	s_add_i32 s1, s1, -16
	s_cmp_lg_u32 s1, 0
	v_mad_u64_u32 v[46:47], s[44:45], v78, s24, v[6:7]
	v_mad_u64_u32 v[48:49], s[44:45], v4, s24, v[6:7]
	v_mad_u64_u32 v[50:51], s[44:45], v80, s24, v[6:7]
	v_mad_u64_u32 v[52:53], s[44:45], v79, s24, v[6:7]
	v_mad_u64_u32 v[54:55], s[44:45], v82, s24, v[6:7]
	v_mad_u64_u32 v[56:57], s[44:45], v81, s24, v[6:7]
	v_mad_u64_u32 v[58:59], s[44:45], v84, s24, v[6:7]
	v_mad_u64_u32 v[60:61], s[44:45], v83, s24, v[6:7]
	v_mad_u64_u32 v[62:63], s[44:45], v86, s24, v[6:7]
	v_mad_u64_u32 v[64:65], s[44:45], v85, s24, v[6:7]
	v_mad_u64_u32 v[66:67], s[44:45], v88, s24, v[6:7]
	v_mad_u64_u32 v[68:69], s[44:45], v87, s24, v[6:7]
	v_mad_u64_u32 v[70:71], s[44:45], v90, s24, v[6:7]
	v_mad_u64_u32 v[72:73], s[44:45], v89, s24, v[6:7]
	v_mad_u64_u32 v[74:75], s[44:45], v92, s24, v[6:7]
	v_mad_u64_u32 v[76:77], s[44:45], v91, s24, v[6:7]
	s_waitcnt vmcnt(16)
; #define LAS __attribute__((address_space(3)))
; #define LAS __attribute__((address_space(3)))
; __device__ __forceinline__ unsigned pkbf(float lo, float hi) { return pg8::cvt_pk_bf16(lo, hi); }
; __device__ __forceinline__ void transpose_item(const float* W, int K, int N, bf16_t* WT, int k0, int n_src, int n_dst, LAS float* scr, int lane) {
;     ...
;     for (int i = 0; i < 32; ++i) { const int kk = 2 * i + (lane >> 5); scr[kk * 33 + (lane & 31)] = W[(size_t)(k0 + kk) * N + n_src + (lane & 31)]; }
;     asm volatile("s_waitcnt lgkmcnt(0)" ::: "memory");
;     const int c = lane & 7;
; #pragma unroll
;     for (int j = 0; j < 4; ++j) {
;         const int n = (lane >> 3) + 8 * j; const LAS float* s = scr + (8 * c) * 33 + n;
;         u32x4 o; o.x = pkbf(s[0 * 33], s[1 * 33]); o.y = pkbf(s[2 * 33], s[3 * 33]); o.z = pkbf(s[4 * 33], s[5 * 33]); o.w = pkbf(s[6 * 33], s[7 * 33]);
;         *(u32x4*)(WT + (size_t)(n_dst + n) * K + k0 + 8 * c) = o;
;     }
	ds_write_b32 v46, v93
	ds_write_b32 v48, v94
	ds_write_b32 v50, v95
	ds_write_b32 v52, v96
	ds_write_b32 v54, v97
	ds_write_b32 v56, v98
	ds_write_b32 v58, v99
	ds_write_b32 v60, v100
	ds_write_b32 v62, v101
	ds_write_b32 v64, v102
	ds_write_b32 v66, v103
	ds_write_b32 v68, v104
	ds_write_b32 v70, v105
	ds_write_b32 v72, v106
	ds_write_b32 v74, v107
	ds_write_b32 v76, v108
	v_mad_u64_u32 v[110:111], s[44:45], v142, s24, v[6:7]
	v_mad_u64_u32 v[112:113], s[44:45], v174, s24, v[6:7]
	v_mad_u64_u32 v[114:115], s[44:45], v144, s24, v[6:7]
	v_mad_u64_u32 v[116:117], s[44:45], v143, s24, v[6:7]
	v_mad_u64_u32 v[118:119], s[44:45], v146, s24, v[6:7]
	v_mad_u64_u32 v[120:121], s[44:45], v145, s24, v[6:7]
	v_mad_u64_u32 v[122:123], s[44:45], v148, s24, v[6:7]
	v_mad_u64_u32 v[124:125], s[44:45], v147, s24, v[6:7]
	v_mad_u64_u32 v[126:127], s[44:45], v150, s24, v[6:7]
	v_mad_u64_u32 v[128:129], s[44:45], v149, s24, v[6:7]
	v_mad_u64_u32 v[130:131], s[44:45], v152, s24, v[6:7]
	v_mad_u64_u32 v[132:133], s[44:45], v151, s24, v[6:7]
	v_mad_u64_u32 v[134:135], s[44:45], v154, s24, v[6:7]
	v_mad_u64_u32 v[136:137], s[44:45], v153, s24, v[6:7]
	v_mad_u64_u32 v[138:139], s[44:45], v156, s24, v[6:7]
	v_mad_u64_u32 v[140:141], s[44:45], v155, s24, v[6:7]
	s_waitcnt vmcnt(0)
	ds_write_b32 v110, v157
	ds_write_b32 v112, v158
	ds_write_b32 v114, v159
	ds_write_b32 v116, v160
	ds_write_b32 v118, v161
	ds_write_b32 v120, v162
	ds_write_b32 v122, v163
	ds_write_b32 v124, v164
	ds_write_b32 v126, v165
	ds_write_b32 v128, v166
	ds_write_b32 v130, v167
	ds_write_b32 v132, v168
	ds_write_b32 v134, v169
	ds_write_b32 v136, v170
	ds_write_b32 v138, v171
	ds_write_b32 v140, v172
	s_waitcnt lgkmcnt(0)
	ds_read2_b32 v[36:37], v38 offset1:33
	s_waitcnt lgkmcnt(0)
	v_cvt_pk_bf16_f32 v46, v36, v37
	ds_read2_b32 v[36:37], v38 offset0:66 offset1:99
	s_waitcnt lgkmcnt(0)
	v_cvt_pk_bf16_f32 v47, v36, v37
	ds_read2_b32 v[36:37], v38 offset0:132 offset1:165
	v_lshlrev_b32_e32 v4, 1, v34
	v_or_b32_e32 v3, v7, v35
	s_waitcnt lgkmcnt(0)
	v_cvt_pk_bf16_f32 v48, v36, v37
	ds_read2_b32 v[36:37], v38 offset0:198 offset1:231
	v_lshl_add_u64 v[50:51], v[22:23], 0, v[4:5]
	v_lshlrev_b32_e32 v4, 11, v3
	s_waitcnt lgkmcnt(0)
	v_cvt_pk_bf16_f32 v49, v36, v37
	ds_read2_b32 v[36:37], v38 offset0:8 offset1:41
	v_lshl_add_u64 v[52:53], v[50:51], 0, v[4:5]
	global_store_dwordx4 v[52:53], v[46:49], off
	v_or_b32_e32 v3, v39, v35
	v_lshlrev_b32_e32 v4, 11, v3
	s_waitcnt lgkmcnt(0)
	v_cvt_pk_bf16_f32 v46, v36, v37
	ds_read2_b32 v[36:37], v38 offset0:74 offset1:107
	s_waitcnt lgkmcnt(0)
	v_cvt_pk_bf16_f32 v47, v36, v37
	ds_read2_b32 v[36:37], v38 offset0:140 offset1:173
	s_waitcnt lgkmcnt(0)
	v_cvt_pk_bf16_f32 v48, v36, v37
	ds_read2_b32 v[36:37], v38 offset0:206 offset1:239
	s_waitcnt lgkmcnt(0)
	v_cvt_pk_bf16_f32 v49, v36, v37
	ds_read2_b32 v[36:37], v38 offset0:16 offset1:49
	v_lshl_add_u64 v[52:53], v[50:51], 0, v[4:5]
	global_store_dwordx4 v[52:53], v[46:49], off
	v_or_b32_e32 v3, v40, v35
	v_lshlrev_b32_e32 v4, 11, v3
	s_waitcnt lgkmcnt(0)
	v_cvt_pk_bf16_f32 v46, v36, v37
	ds_read2_b32 v[36:37], v38 offset0:82 offset1:115
	s_waitcnt lgkmcnt(0)
	v_cvt_pk_bf16_f32 v47, v36, v37
	ds_read2_b32 v[36:37], v38 offset0:148 offset1:181
	s_waitcnt lgkmcnt(0)
	v_cvt_pk_bf16_f32 v48, v36, v37
	ds_read2_b32 v[36:37], v38 offset0:214 offset1:247
	s_waitcnt lgkmcnt(0)
	v_cvt_pk_bf16_f32 v49, v36, v37
	ds_read2_b32 v[36:37], v38 offset0:24 offset1:57
	v_lshl_add_u64 v[52:53], v[50:51], 0, v[4:5]
	v_or_b32_e32 v3, v41, v35
	global_store_dwordx4 v[52:53], v[46:49], off
	v_lshlrev_b32_e32 v4, 11, v3
	v_lshl_add_u64 v[34:35], v[50:51], 0, v[4:5]
	s_waitcnt lgkmcnt(0)
	v_cvt_pk_bf16_f32 v46, v36, v37
	ds_read2_b32 v[36:37], v38 offset0:90 offset1:123
	s_waitcnt lgkmcnt(0)
	v_cvt_pk_bf16_f32 v47, v36, v37
	ds_read2_b32 v[36:37], v38 offset0:156 offset1:189
	s_waitcnt lgkmcnt(0)
	v_cvt_pk_bf16_f32 v48, v36, v37
	ds_read2_b32 v[36:37], v38 offset0:222 offset1:255
	s_waitcnt lgkmcnt(0)
	v_cvt_pk_bf16_f32 v49, v36, v37
	global_store_dwordx4 v[34:35], v[46:49], off
	s_waitcnt lgkmcnt(0)

; __device__ __forceinline__ void transpose_item(const float* W, int K, int N, bf16_t* WT, int k0, int n_src, int n_dst, LAS float* scr, int lane) {
;     ...
;     for (int i = 0; i < 32; ++i) { const int kk = 2 * i + (lane >> 5); scr[kk * 33 + (lane & 31)] = W[(size_t)(k0 + kk) * N + n_src + (lane & 31)]; }
; __device__ __forceinline__ void convert_layer(const Params& p, LAS unsigned char* lds, int l, int gwi, int ngw, int lane, int wid) {
;     ...
;         if (rr < 512) { const int kb = rr / 32, nb = rr % 32; transpose_item(p.w_out + (size_t)l * DM * DM, DM, DM, (bf16_t*)(wl + W_OUT), 64 * kb, 32 * nb, 32 * nb, scr, lane); continue; } rr -= 512;
.LBB0_43:
	s_lshl_b32 s23, s20, 1
	s_lshl_b32 s43, s21, 1
	v_or_b32_e32 v4, s23, v1
	v_or_b32_e32 v35, s43, v2
	s_add_i32 s44, s23, 4
	s_add_i32 s45, s43, 4
	s_add_i32 s46, s23, 8
	s_add_i32 s47, s43, 8
	s_add_i32 s48, s23, 12
	s_add_i32 s49, s43, 12
	s_add_i32 s50, s23, 16
	s_add_i32 s51, s43, 16
	s_add_i32 s52, s23, 20
	s_add_i32 s53, s43, 20
	s_add_i32 s54, s23, 24
	s_add_i32 s55, s43, 24
	s_add_i32 s23, s23, 28
	s_add_i32 s43, s43, 28
	v_add_u32_e32 v50, v35, v34
	v_or_b32_e32 v47, s44, v1
	v_or_b32_e32 v80, s45, v2
	v_or_b32_e32 v81, s46, v1
	v_or_b32_e32 v82, s47, v2
	v_or_b32_e32 v83, s48, v1
	v_or_b32_e32 v84, s49, v2
	v_or_b32_e32 v85, s50, v1
	v_or_b32_e32 v86, s51, v2
	v_or_b32_e32 v87, s52, v1
	v_or_b32_e32 v88, s53, v2
	v_or_b32_e32 v89, s54, v1
	v_or_b32_e32 v90, s55, v2
	v_or_b32_e32 v91, s23, v1
	v_or_b32_e32 v92, s43, v2
	v_add_u32_e32 v48, v4, v3
	v_ashrrev_i32_e32 v51, 31, v50
	v_add_u32_e32 v52, v47, v3
	v_add_u32_e32 v54, v80, v34
	v_add_u32_e32 v56, v81, v3
	v_add_u32_e32 v58, v82, v34
	v_add_u32_e32 v60, v83, v3
	v_add_u32_e32 v62, v84, v34
	v_add_u32_e32 v64, v85, v3
	v_add_u32_e32 v66, v86, v34
	v_add_u32_e32 v68, v87, v3
	v_add_u32_e32 v70, v88, v34
	v_add_u32_e32 v72, v89, v3
	v_add_u32_e32 v74, v90, v34
	v_add_u32_e32 v76, v91, v3
	v_add_u32_e32 v78, v92, v34
	v_ashrrev_i32_e32 v49, 31, v48
	v_lshlrev_b64 v[50:51], 12, v[50:51]
	v_ashrrev_i32_e32 v55, 31, v54
	v_ashrrev_i32_e32 v53, 31, v52
	v_ashrrev_i32_e32 v59, 31, v58
	v_ashrrev_i32_e32 v57, 31, v56
	v_ashrrev_i32_e32 v63, 31, v62
	v_ashrrev_i32_e32 v61, 31, v60
	v_ashrrev_i32_e32 v67, 31, v66
	v_ashrrev_i32_e32 v65, 31, v64
	v_ashrrev_i32_e32 v71, 31, v70
	v_ashrrev_i32_e32 v69, 31, v68
	v_ashrrev_i32_e32 v75, 31, v74
	v_ashrrev_i32_e32 v73, 31, v72
	v_ashrrev_i32_e32 v79, 31, v78
	v_ashrrev_i32_e32 v77, 31, v76
	v_lshlrev_b64 v[48:49], 12, v[48:49]
	v_lshl_add_u64 v[50:51], v[36:37], 0, v[50:51]
	v_lshlrev_b64 v[52:53], 12, v[52:53]
	v_lshlrev_b64 v[54:55], 12, v[54:55]
	v_lshlrev_b64 v[56:57], 12, v[56:57]
	v_lshlrev_b64 v[58:59], 12, v[58:59]
	v_lshlrev_b64 v[60:61], 12, v[60:61]
	v_lshlrev_b64 v[62:63], 12, v[62:63]
	v_lshlrev_b64 v[64:65], 12, v[64:65]
	v_lshlrev_b64 v[66:67], 12, v[66:67]
	v_lshlrev_b64 v[68:69], 12, v[68:69]
	v_lshlrev_b64 v[70:71], 12, v[70:71]
	v_lshlrev_b64 v[72:73], 12, v[72:73]
	v_lshlrev_b64 v[74:75], 12, v[74:75]
	v_lshlrev_b64 v[76:77], 12, v[76:77]
	v_lshlrev_b64 v[78:79], 12, v[78:79]
	v_lshl_add_u64 v[48:49], v[36:37], 0, v[48:49]
	v_lshl_add_u64 v[54:55], v[36:37], 0, v[54:55]
	v_lshl_add_u64 v[52:53], v[36:37], 0, v[52:53]
	v_lshl_add_u64 v[58:59], v[36:37], 0, v[58:59]
	v_lshl_add_u64 v[56:57], v[36:37], 0, v[56:57]
	v_lshl_add_u64 v[62:63], v[36:37], 0, v[62:63]
	v_lshl_add_u64 v[60:61], v[36:37], 0, v[60:61]
	v_lshl_add_u64 v[66:67], v[36:37], 0, v[66:67]
	v_lshl_add_u64 v[64:65], v[36:37], 0, v[64:65]
	v_lshl_add_u64 v[70:71], v[36:37], 0, v[70:71]
	v_lshl_add_u64 v[68:69], v[36:37], 0, v[68:69]
	v_lshl_add_u64 v[74:75], v[36:37], 0, v[74:75]
	v_lshl_add_u64 v[72:73], v[36:37], 0, v[72:73]
	v_lshl_add_u64 v[78:79], v[36:37], 0, v[78:79]
	v_lshl_add_u64 v[76:77], v[36:37], 0, v[76:77]
	global_load_dword v93, v[50:51], off
	global_load_dword v94, v[48:49], off
	global_load_dword v95, v[54:55], off
	global_load_dword v96, v[52:53], off
	global_load_dword v97, v[58:59], off
	global_load_dword v98, v[56:57], off
	global_load_dword v99, v[62:63], off
	global_load_dword v100, v[60:61], off
	global_load_dword v101, v[66:67], off
	global_load_dword v102, v[64:65], off
	global_load_dword v103, v[70:71], off
	global_load_dword v104, v[68:69], off
	global_load_dword v105, v[74:75], off
	global_load_dword v106, v[72:73], off
	global_load_dword v107, v[78:79], off
	global_load_dword v108, v[76:77], off
	s_add_i32 s21, s21, 16
	s_add_i32 s20, s20, 16
	s_add_i32 s22, s22, -16
	s_cmp_lg_u32 s22, 0
	s_lshl_b32 s23, s20, 1
	s_lshl_b32 s43, s21, 1
	v_or_b32_e32 v174, s23, v1
	v_or_b32_e32 v175, s43, v2
	s_add_i32 s44, s23, 4
	s_add_i32 s45, s43, 4
	s_add_i32 s46, s23, 8
	s_add_i32 s47, s43, 8
	s_add_i32 s48, s23, 12
	s_add_i32 s49, s43, 12
	s_add_i32 s50, s23, 16
	s_add_i32 s51, s43, 16
	s_add_i32 s52, s23, 20
	s_add_i32 s53, s43, 20
	s_add_i32 s54, s23, 24
	s_add_i32 s55, s43, 24
	s_add_i32 s23, s23, 28
	s_add_i32 s43, s43, 28
	v_add_u32_e32 v114, v175, v34
	v_or_b32_e32 v111, s44, v1
	v_or_b32_e32 v144, s45, v2
	v_or_b32_e32 v145, s46, v1
	v_or_b32_e32 v146, s47, v2
	v_or_b32_e32 v147, s48, v1
	v_or_b32_e32 v148, s49, v2
	v_or_b32_e32 v149, s50, v1
	v_or_b32_e32 v150, s51, v2
	v_or_b32_e32 v151, s52, v1
	v_or_b32_e32 v152, s53, v2
	v_or_b32_e32 v153, s54, v1
	v_or_b32_e32 v154, s55, v2
	v_or_b32_e32 v155, s23, v1
	v_or_b32_e32 v156, s43, v2
	v_add_u32_e32 v112, v174, v3
	v_ashrrev_i32_e32 v115, 31, v114
	v_add_u32_e32 v116, v111, v3
	v_add_u32_e32 v118, v144, v34
	v_add_u32_e32 v120, v145, v3
	v_add_u32_e32 v122, v146, v34
	v_add_u32_e32 v124, v147, v3
	v_add_u32_e32 v126, v148, v34
	v_add_u32_e32 v128, v149, v3
	v_add_u32_e32 v130, v150, v34
	v_add_u32_e32 v132, v151, v3
	v_add_u32_e32 v134, v152, v34
	v_add_u32_e32 v136, v153, v3
	v_add_u32_e32 v138, v154, v34
	v_add_u32_e32 v140, v155, v3
	v_add_u32_e32 v142, v156, v34
	v_ashrrev_i32_e32 v113, 31, v112
	v_lshlrev_b64 v[114:115], 12, v[114:115]
	v_ashrrev_i32_e32 v119, 31, v118
	v_ashrrev_i32_e32 v117, 31, v116
	v_ashrrev_i32_e32 v123, 31, v122
	v_ashrrev_i32_e32 v121, 31, v120
	v_ashrrev_i32_e32 v127, 31, v126
	v_ashrrev_i32_e32 v125, 31, v124
	v_ashrrev_i32_e32 v131, 31, v130
	v_ashrrev_i32_e32 v129, 31, v128
	v_ashrrev_i32_e32 v135, 31, v134
	v_ashrrev_i32_e32 v133, 31, v132
; __device__ __forceinline__ void transpose_item(const float* W, int K, int N, bf16_t* WT, int k0, int n_src, int n_dst, LAS float* scr, int lane) {
;     ...
;     for (int i = 0; i < 32; ++i) { const int kk = 2 * i + (lane >> 5); scr[kk * 33 + (lane & 31)] = W[(size_t)(k0 + kk) * N + n_src + (lane & 31)]; }
	v_ashrrev_i32_e32 v139, 31, v138
	v_ashrrev_i32_e32 v137, 31, v136
	v_ashrrev_i32_e32 v143, 31, v142
	v_ashrrev_i32_e32 v141, 31, v140
	v_lshlrev_b64 v[112:113], 12, v[112:113]
	v_lshl_add_u64 v[114:115], v[36:37], 0, v[114:115]
	v_lshlrev_b64 v[116:117], 12, v[116:117]
	v_lshlrev_b64 v[118:119], 12, v[118:119]
	v_lshlrev_b64 v[120:121], 12, v[120:121]
	v_lshlrev_b64 v[122:123], 12, v[122:123]
	v_lshlrev_b64 v[124:125], 12, v[124:125]
	v_lshlrev_b64 v[126:127], 12, v[126:127]
	v_lshlrev_b64 v[128:129], 12, v[128:129]
	v_lshlrev_b64 v[130:131], 12, v[130:131]
	v_lshlrev_b64 v[132:133], 12, v[132:133]
	v_lshlrev_b64 v[134:135], 12, v[134:135]
	v_lshlrev_b64 v[136:137], 12, v[136:137]
	v_lshlrev_b64 v[138:139], 12, v[138:139]
	v_lshlrev_b64 v[140:141], 12, v[140:141]
	v_lshlrev_b64 v[142:143], 12, v[142:143]
	v_lshl_add_u64 v[112:113], v[36:37], 0, v[112:113]
	v_lshl_add_u64 v[118:119], v[36:37], 0, v[118:119]
	v_lshl_add_u64 v[116:117], v[36:37], 0, v[116:117]
	v_lshl_add_u64 v[122:123], v[36:37], 0, v[122:123]
	v_lshl_add_u64 v[120:121], v[36:37], 0, v[120:121]
	v_lshl_add_u64 v[126:127], v[36:37], 0, v[126:127]
	v_lshl_add_u64 v[124:125], v[36:37], 0, v[124:125]
	v_lshl_add_u64 v[130:131], v[36:37], 0, v[130:131]
	v_lshl_add_u64 v[128:129], v[36:37], 0, v[128:129]
	v_lshl_add_u64 v[134:135], v[36:37], 0, v[134:135]
	v_lshl_add_u64 v[132:133], v[36:37], 0, v[132:133]
	v_lshl_add_u64 v[138:139], v[36:37], 0, v[138:139]
	v_lshl_add_u64 v[136:137], v[36:37], 0, v[136:137]
	v_lshl_add_u64 v[142:143], v[36:37], 0, v[142:143]
	v_lshl_add_u64 v[140:141], v[36:37], 0, v[140:141]
	global_load_dword v157, v[114:115], off
	global_load_dword v158, v[112:113], off
	global_load_dword v159, v[118:119], off
	global_load_dword v160, v[116:117], off
	global_load_dword v161, v[122:123], off
	global_load_dword v162, v[120:121], off
	global_load_dword v163, v[126:127], off
	global_load_dword v164, v[124:125], off
	global_load_dword v165, v[130:131], off
	global_load_dword v166, v[128:129], off
	global_load_dword v167, v[134:135], off
	global_load_dword v168, v[132:133], off
	global_load_dword v169, v[138:139], off
	global_load_dword v170, v[136:137], off
	global_load_dword v171, v[142:143], off
	global_load_dword v172, v[140:141], off
	s_add_i32 s21, s21, 16
	s_add_i32 s20, s20, 16
	s_add_i32 s22, s22, -16
	s_cmp_lg_u32 s22, 0
	v_mad_u64_u32 v[48:49], s[44:45], v35, s24, v[6:7]
	v_mad_u64_u32 v[50:51], s[44:45], v4, s24, v[6:7]
	v_mad_u64_u32 v[52:53], s[44:45], v80, s24, v[6:7]
	v_mad_u64_u32 v[54:55], s[44:45], v47, s24, v[6:7]
	v_mad_u64_u32 v[56:57], s[44:45], v82, s24, v[6:7]
	v_mad_u64_u32 v[58:59], s[44:45], v81, s24, v[6:7]
	v_mad_u64_u32 v[60:61], s[44:45], v84, s24, v[6:7]
	v_mad_u64_u32 v[62:63], s[44:45], v83, s24, v[6:7]
	v_mad_u64_u32 v[64:65], s[44:45], v86, s24, v[6:7]
	v_mad_u64_u32 v[66:67], s[44:45], v85, s24, v[6:7]
	v_mad_u64_u32 v[68:69], s[44:45], v88, s24, v[6:7]
	v_mad_u64_u32 v[70:71], s[44:45], v87, s24, v[6:7]
	v_mad_u64_u32 v[72:73], s[44:45], v90, s24, v[6:7]
	v_mad_u64_u32 v[74:75], s[44:45], v89, s24, v[6:7]
	v_mad_u64_u32 v[76:77], s[44:45], v92, s24, v[6:7]
	v_mad_u64_u32 v[78:79], s[44:45], v91, s24, v[6:7]
	s_waitcnt vmcnt(16)
; #define LAS __attribute__((address_space(3)))
; #define LAS __attribute__((address_space(3)))
; __device__ __forceinline__ unsigned pkbf(float lo, float hi) { return pg8::cvt_pk_bf16(lo, hi); }
; __device__ __forceinline__ void transpose_item(const float* W, int K, int N, bf16_t* WT, int k0, int n_src, int n_dst, LAS float* scr, int lane) {
;     ...
;     for (int i = 0; i < 32; ++i) { const int kk = 2 * i + (lane >> 5); scr[kk * 33 + (lane & 31)] = W[(size_t)(k0 + kk) * N + n_src + (lane & 31)]; }
;     asm volatile("s_waitcnt lgkmcnt(0)" ::: "memory");
;     const int c = lane & 7;
; #pragma unroll
;     for (int j = 0; j < 4; ++j) {
;         const int n = (lane >> 3) + 8 * j; const LAS float* s = scr + (8 * c) * 33 + n;
;         u32x4 o; o.x = pkbf(s[0 * 33], s[1 * 33]); o.y = pkbf(s[2 * 33], s[3 * 33]); o.z = pkbf(s[4 * 33], s[5 * 33]); o.w = pkbf(s[6 * 33], s[7 * 33]);
;         *(u32x4*)(WT + (size_t)(n_dst + n) * K + k0 + 8 * c) = o;
;     }
	ds_write_b32 v48, v93
	ds_write_b32 v50, v94
	ds_write_b32 v52, v95
	ds_write_b32 v54, v96
	ds_write_b32 v56, v97
	ds_write_b32 v58, v98
	ds_write_b32 v60, v99
	ds_write_b32 v62, v100
	ds_write_b32 v64, v101
	ds_write_b32 v66, v102
	ds_write_b32 v68, v103
	ds_write_b32 v70, v104
	ds_write_b32 v72, v105
	ds_write_b32 v74, v106
	ds_write_b32 v76, v107
	ds_write_b32 v78, v108
	v_mad_u64_u32 v[112:113], s[44:45], v175, s24, v[6:7]
	v_mad_u64_u32 v[114:115], s[44:45], v174, s24, v[6:7]
	v_mad_u64_u32 v[116:117], s[44:45], v144, s24, v[6:7]
	v_mad_u64_u32 v[118:119], s[44:45], v111, s24, v[6:7]
	v_mad_u64_u32 v[120:121], s[44:45], v146, s24, v[6:7]
	v_mad_u64_u32 v[122:123], s[44:45], v145, s24, v[6:7]
	v_mad_u64_u32 v[124:125], s[44:45], v148, s24, v[6:7]
	v_mad_u64_u32 v[126:127], s[44:45], v147, s24, v[6:7]
	v_mad_u64_u32 v[128:129], s[44:45], v150, s24, v[6:7]
	v_mad_u64_u32 v[130:131], s[44:45], v149, s24, v[6:7]
	v_mad_u64_u32 v[132:133], s[44:45], v152, s24, v[6:7]
	v_mad_u64_u32 v[134:135], s[44:45], v151, s24, v[6:7]
	v_mad_u64_u32 v[136:137], s[44:45], v154, s24, v[6:7]
	v_mad_u64_u32 v[138:139], s[44:45], v153, s24, v[6:7]
	v_mad_u64_u32 v[140:141], s[44:45], v156, s24, v[6:7]
	v_mad_u64_u32 v[142:143], s[44:45], v155, s24, v[6:7]
	s_waitcnt vmcnt(0)
	ds_write_b32 v112, v157
	ds_write_b32 v114, v158
	ds_write_b32 v116, v159
	ds_write_b32 v118, v160
	ds_write_b32 v120, v161
	ds_write_b32 v122, v162
	ds_write_b32 v124, v163
	ds_write_b32 v126, v164
	ds_write_b32 v128, v165
	ds_write_b32 v130, v166
	ds_write_b32 v132, v167
	ds_write_b32 v134, v168
	ds_write_b32 v136, v169
	ds_write_b32 v138, v170
	ds_write_b32 v140, v171
	ds_write_b32 v142, v172
	s_waitcnt lgkmcnt(0)
	ds_read2_b32 v[36:37], v38 offset1:33
	s_waitcnt lgkmcnt(0)
	v_cvt_pk_bf16_f32 v48, v36, v37
	ds_read2_b32 v[36:37], v38 offset0:66 offset1:99
	s_waitcnt lgkmcnt(0)
	v_cvt_pk_bf16_f32 v49, v36, v37
	ds_read2_b32 v[36:37], v38 offset0:132 offset1:165
	v_mov_b32_e32 v35, v5
	v_or_b32_e32 v3, v46, v7
	s_waitcnt lgkmcnt(0)
	v_cvt_pk_bf16_f32 v50, v36, v37
	ds_read2_b32 v[36:37], v38 offset0:198 offset1:231
	v_lshl_add_u64 v[52:53], v[34:35], 1, v[24:25]
	v_lshlrev_b32_e32 v4, 11, v3
	s_waitcnt lgkmcnt(0)
	v_cvt_pk_bf16_f32 v51, v36, v37
	ds_read2_b32 v[36:37], v38 offset0:8 offset1:41
	v_lshl_add_u64 v[34:35], v[52:53], 0, v[4:5]
	global_store_dwordx4 v[34:35], v[48:51], off
	s_waitcnt lgkmcnt(0)
	v_cvt_pk_bf16_f32 v34, v36, v37
	ds_read2_b32 v[36:37], v38 offset0:74 offset1:107
	v_or_b32_e32 v3, v46, v39
	s_waitcnt lgkmcnt(0)
	v_cvt_pk_bf16_f32 v35, v36, v37
	ds_read2_b32 v[36:37], v38 offset0:140 offset1:173
	v_lshlrev_b32_e32 v4, 11, v3
	s_waitcnt lgkmcnt(0)
	v_cvt_pk_bf16_f32 v36, v36, v37
	ds_read2_b32 v[48:49], v38 offset0:206 offset1:239
	s_waitcnt lgkmcnt(0)
	v_cvt_pk_bf16_f32 v37, v48, v49
	v_lshl_add_u64 v[50:51], v[52:53], 0, v[4:5]
	ds_read2_b32 v[48:49], v38 offset0:16 offset1:49
	global_store_dwordx4 v[50:51], v[34:37], off
	v_or_b32_e32 v3, v46, v40
	v_lshlrev_b32_e32 v4, 11, v3
	s_waitcnt lgkmcnt(0)
	v_cvt_pk_bf16_f32 v34, v48, v49
	ds_read2_b32 v[36:37], v38 offset0:82 offset1:115
	s_waitcnt lgkmcnt(0)
	v_cvt_pk_bf16_f32 v35, v36, v37
	ds_read2_b32 v[36:37], v38 offset0:148 offset1:181
	s_waitcnt lgkmcnt(0)
	v_cvt_pk_bf16_f32 v36, v36, v37
	ds_read2_b32 v[48:49], v38 offset0:214 offset1:247
	s_waitcnt lgkmcnt(0)
	v_cvt_pk_bf16_f32 v37, v48, v49
	v_lshl_add_u64 v[50:51], v[52:53], 0, v[4:5]
	v_or_b32_e32 v3, v46, v41
	ds_read2_b32 v[48:49], v38 offset0:24 offset1:57
	global_store_dwordx4 v[50:51], v[34:37], off
	v_lshlrev_b32_e32 v4, 11, v3
	v_lshl_add_u64 v[46:47], v[52:53], 0, v[4:5]
	s_waitcnt lgkmcnt(0)
	v_cvt_pk_bf16_f32 v34, v48, v49
	ds_read2_b32 v[36:37], v38 offset0:90 offset1:123
	s_waitcnt lgkmcnt(0)
	v_cvt_pk_bf16_f32 v35, v36, v37
	ds_read2_b32 v[36:37], v38 offset0:156 offset1:189
	s_waitcnt lgkmcnt(0)
	v_cvt_pk_bf16_f32 v36, v36, v37
	ds_read2_b32 v[48:49], v38 offset0:222 offset1:255
	s_waitcnt lgkmcnt(0)
	v_cvt_pk_bf16_f32 v37, v48, v49
	global_store_dwordx4 v[46:47], v[34:37], off
	s_waitcnt lgkmcnt(0)

; __device__ __forceinline__ void transpose_item(const float* W, int K, int N, bf16_t* WT, int k0, int n_src, int n_dst, LAS float* scr, int lane) {
; #pragma unroll 8
;     for (int i = 0; i < 32; ++i) { const int kk = 2 * i + (lane >> 5); scr[kk * 33 + (lane & 31)] = W[(size_t)(k0 + kk) * N + n_src + (lane & 31)]; }
.LBB0_58:
	s_lshl_b32 s21, s0, 1
	s_lshl_b32 s22, s1, 1
	v_or_b32_e32 v35, s21, v1
	v_or_b32_e32 v78, s22, v2
	s_add_i32 s23, s21, 4
	s_add_i32 s43, s22, 4
	s_add_i32 s44, s21, 8
	s_add_i32 s45, s22, 8
	s_add_i32 s46, s21, 12
	s_add_i32 s47, s22, 12
	s_add_i32 s48, s21, 16
	s_add_i32 s49, s22, 16
	s_add_i32 s50, s21, 20
	s_add_i32 s51, s22, 20
	s_add_i32 s52, s21, 24
	s_add_i32 s53, s22, 24
	s_add_i32 s21, s21, 28
	s_add_i32 s22, s22, 28
	v_add_u32_e32 v46, v78, v34
	v_or_b32_e32 v79, s23, v1
	v_or_b32_e32 v80, s43, v2
	v_or_b32_e32 v81, s44, v1
	v_or_b32_e32 v82, s45, v2
	v_or_b32_e32 v83, s46, v1
	v_or_b32_e32 v84, s47, v2
	v_or_b32_e32 v85, s48, v1
	v_or_b32_e32 v86, s49, v2
	v_or_b32_e32 v87, s50, v1
	v_or_b32_e32 v88, s51, v2
	v_or_b32_e32 v89, s52, v1
	v_or_b32_e32 v90, s53, v2
	v_or_b32_e32 v91, s21, v1
	v_or_b32_e32 v92, s22, v2
	v_add_u32_e32 v48, v35, v3
	v_mad_i64_i32 v[46:47], s[22:23], v46, s41, v[36:37]
	v_add_u32_e32 v52, v79, v3
	v_add_u32_e32 v50, v80, v34
	v_add_u32_e32 v56, v81, v3
	v_add_u32_e32 v54, v82, v34
	v_add_u32_e32 v60, v83, v3
	v_add_u32_e32 v58, v84, v34
	v_add_u32_e32 v64, v85, v3
	v_add_u32_e32 v62, v86, v34
	v_add_u32_e32 v68, v87, v3
	v_add_u32_e32 v66, v88, v34
	v_add_u32_e32 v72, v89, v3
	v_add_u32_e32 v70, v90, v34
	v_add_u32_e32 v76, v91, v3
	v_add_u32_e32 v74, v92, v34
	v_mad_i64_i32 v[48:49], s[22:23], v48, s41, v[36:37]
	v_mad_i64_i32 v[50:51], s[22:23], v50, s41, v[36:37]
	v_mad_i64_i32 v[52:53], s[22:23], v52, s41, v[36:37]
	v_mad_i64_i32 v[54:55], s[22:23], v54, s41, v[36:37]
	v_mad_i64_i32 v[56:57], s[22:23], v56, s41, v[36:37]
	v_mad_i64_i32 v[58:59], s[22:23], v58, s41, v[36:37]
	v_mad_i64_i32 v[60:61], s[22:23], v60, s41, v[36:37]
	v_mad_i64_i32 v[62:63], s[22:23], v62, s41, v[36:37]
	v_mad_i64_i32 v[64:65], s[22:23], v64, s41, v[36:37]
	v_mad_i64_i32 v[66:67], s[22:23], v66, s41, v[36:37]
	v_mad_i64_i32 v[68:69], s[22:23], v68, s41, v[36:37]
	v_mad_i64_i32 v[70:71], s[22:23], v70, s41, v[36:37]
	v_mad_i64_i32 v[72:73], s[22:23], v72, s41, v[36:37]
	v_mad_i64_i32 v[74:75], s[22:23], v74, s41, v[36:37]
	v_mad_i64_i32 v[76:77], s[22:23], v76, s41, v[36:37]
	global_load_dword v93, v[46:47], off
	global_load_dword v94, v[48:49], off
	global_load_dword v95, v[50:51], off
	global_load_dword v96, v[52:53], off
	global_load_dword v97, v[54:55], off
	global_load_dword v98, v[56:57], off
	global_load_dword v99, v[58:59], off
	global_load_dword v100, v[60:61], off
	global_load_dword v101, v[62:63], off
	global_load_dword v102, v[64:65], off
	global_load_dword v103, v[66:67], off
	global_load_dword v104, v[68:69], off
	global_load_dword v105, v[70:71], off
	global_load_dword v106, v[72:73], off
	global_load_dword v107, v[74:75], off
	global_load_dword v108, v[76:77], off
	s_add_i32 s1, s1, 16
	s_add_i32 s0, s0, 16
	s_add_i32 s20, s20, -16
	s_cmp_lg_u32 s20, 0
	s_lshl_b32 s21, s0, 1
	s_lshl_b32 s22, s1, 1
	v_or_b32_e32 v174, s21, v1
	v_or_b32_e32 v142, s22, v2
	s_add_i32 s23, s21, 4
	s_add_i32 s43, s22, 4
	s_add_i32 s44, s21, 8
	s_add_i32 s45, s22, 8
	s_add_i32 s46, s21, 12
	s_add_i32 s47, s22, 12
	s_add_i32 s48, s21, 16
	s_add_i32 s49, s22, 16
	s_add_i32 s50, s21, 20
	s_add_i32 s51, s22, 20
	s_add_i32 s52, s21, 24
	s_add_i32 s53, s22, 24
	s_add_i32 s21, s21, 28
	s_add_i32 s22, s22, 28
	v_add_u32_e32 v110, v142, v34
	v_or_b32_e32 v143, s23, v1
	v_or_b32_e32 v144, s43, v2
	v_or_b32_e32 v145, s44, v1
	v_or_b32_e32 v146, s45, v2
	v_or_b32_e32 v147, s46, v1
	v_or_b32_e32 v148, s47, v2
	v_or_b32_e32 v149, s48, v1
	v_or_b32_e32 v150, s49, v2
	v_or_b32_e32 v151, s50, v1
	v_or_b32_e32 v152, s51, v2
	v_or_b32_e32 v153, s52, v1
	v_or_b32_e32 v154, s53, v2
	v_or_b32_e32 v155, s21, v1
	v_or_b32_e32 v156, s22, v2
	v_add_u32_e32 v112, v174, v3
	v_mad_i64_i32 v[110:111], s[22:23], v110, s41, v[36:37]
	v_add_u32_e32 v116, v143, v3
	v_add_u32_e32 v114, v144, v34
	v_add_u32_e32 v120, v145, v3
	v_add_u32_e32 v118, v146, v34
	v_add_u32_e32 v124, v147, v3
	v_add_u32_e32 v122, v148, v34
	v_add_u32_e32 v128, v149, v3
	v_add_u32_e32 v126, v150, v34
	v_add_u32_e32 v132, v151, v3
	v_add_u32_e32 v130, v152, v34
	v_add_u32_e32 v136, v153, v3
	v_add_u32_e32 v134, v154, v34
	v_add_u32_e32 v140, v155, v3
	v_add_u32_e32 v138, v156, v34
	v_mad_i64_i32 v[112:113], s[22:23], v112, s41, v[36:37]
	v_mad_i64_i32 v[114:115], s[22:23], v114, s41, v[36:37]
	v_mad_i64_i32 v[116:117], s[22:23], v116, s41, v[36:37]
	v_mad_i64_i32 v[118:119], s[22:23], v118, s41, v[36:37]
	v_mad_i64_i32 v[120:121], s[22:23], v120, s41, v[36:37]
	v_mad_i64_i32 v[122:123], s[22:23], v122, s41, v[36:37]
	v_mad_i64_i32 v[124:125], s[22:23], v124, s41, v[36:37]
	v_mad_i64_i32 v[126:127], s[22:23], v126, s41, v[36:37]
	v_mad_i64_i32 v[128:129], s[22:23], v128, s41, v[36:37]
	v_mad_i64_i32 v[130:131], s[22:23], v130, s41, v[36:37]
	v_mad_i64_i32 v[132:133], s[22:23], v132, s41, v[36:37]
	v_mad_i64_i32 v[134:135], s[22:23], v134, s41, v[36:37]
	v_mad_i64_i32 v[136:137], s[22:23], v136, s41, v[36:37]
	v_mad_i64_i32 v[138:139], s[22:23], v138, s41, v[36:37]
	v_mad_i64_i32 v[140:141], s[22:23], v140, s41, v[36:37]
	global_load_dword v157, v[110:111], off
	global_load_dword v158, v[112:113], off
	global_load_dword v159, v[114:115], off
	global_load_dword v160, v[116:117], off
	global_load_dword v161, v[118:119], off
	global_load_dword v162, v[120:121], off
	global_load_dword v163, v[122:123], off
	global_load_dword v164, v[124:125], off
	global_load_dword v165, v[126:127], off
	global_load_dword v166, v[128:129], off
	global_load_dword v167, v[130:131], off
	global_load_dword v168, v[132:133], off
	global_load_dword v169, v[134:135], off
	global_load_dword v170, v[136:137], off
	global_load_dword v171, v[138:139], off
	global_load_dword v172, v[140:141], off
	s_add_i32 s1, s1, 16
	s_add_i32 s0, s0, 16
	s_add_i32 s20, s20, -16
	s_cmp_lg_u32 s20, 0
	v_mad_u64_u32 v[46:47], s[22:23], v78, s24, v[6:7]
	v_mad_u64_u32 v[48:49], s[22:23], v35, s24, v[6:7]
	v_mad_u64_u32 v[50:51], s[22:23], v80, s24, v[6:7]
	v_mad_u64_u32 v[52:53], s[22:23], v79, s24, v[6:7]
	v_mad_u64_u32 v[54:55], s[22:23], v82, s24, v[6:7]
	v_mad_u64_u32 v[56:57], s[22:23], v81, s24, v[6:7]
	v_mad_u64_u32 v[58:59], s[22:23], v84, s24, v[6:7]
	v_mad_u64_u32 v[60:61], s[22:23], v83, s24, v[6:7]
	v_mad_u64_u32 v[62:63], s[22:23], v86, s24, v[6:7]
	v_mad_u64_u32 v[64:65], s[22:23], v85, s24, v[6:7]
	v_mad_u64_u32 v[66:67], s[22:23], v88, s24, v[6:7]
	v_mad_u64_u32 v[68:69], s[22:23], v87, s24, v[6:7]
	v_mad_u64_u32 v[70:71], s[22:23], v90, s24, v[6:7]
	v_mad_u64_u32 v[72:73], s[22:23], v89, s24, v[6:7]
	v_mad_u64_u32 v[74:75], s[22:23], v92, s24, v[6:7]
	v_mad_u64_u32 v[76:77], s[22:23], v91, s24, v[6:7]
	s_waitcnt vmcnt(16)
; #define LAS __attribute__((address_space(3)))
; #define LAS __attribute__((address_space(3)))
; __device__ __forceinline__ unsigned pkbf(float lo, float hi) { return pg8::cvt_pk_bf16(lo, hi); }
; __device__ __forceinline__ void transpose_item(const float* W, int K, int N, bf16_t* WT, int k0, int n_src, int n_dst, LAS float* scr, int lane) {
;     ...
;     for (int i = 0; i < 32; ++i) { const int kk = 2 * i + (lane >> 5); scr[kk * 33 + (lane & 31)] = W[(size_t)(k0 + kk) * N + n_src + (lane & 31)]; }
;     asm volatile("s_waitcnt lgkmcnt(0)" ::: "memory");
;     const int c = lane & 7;
; #pragma unroll
;     for (int j = 0; j < 4; ++j) {
;         const int n = (lane >> 3) + 8 * j; const LAS float* s = scr + (8 * c) * 33 + n;
;         u32x4 o; o.x = pkbf(s[0 * 33], s[1 * 33]); o.y = pkbf(s[2 * 33], s[3 * 33]); o.z = pkbf(s[4 * 33], s[5 * 33]); o.w = pkbf(s[6 * 33], s[7 * 33]);
;         *(u32x4*)(WT + (size_t)(n_dst + n) * K + k0 + 8 * c) = o;
;     }
;     asm volatile("s_waitcnt lgkmcnt(0)" ::: "memory");
	ds_write_b32 v46, v93
	ds_write_b32 v48, v94
	ds_write_b32 v50, v95
	ds_write_b32 v52, v96
	ds_write_b32 v54, v97
	ds_write_b32 v56, v98
	ds_write_b32 v58, v99
	ds_write_b32 v60, v100
	ds_write_b32 v62, v101
	ds_write_b32 v64, v102
	ds_write_b32 v66, v103
	ds_write_b32 v68, v104
	ds_write_b32 v70, v105
	ds_write_b32 v72, v106
	ds_write_b32 v74, v107
	ds_write_b32 v76, v108
	v_mad_u64_u32 v[110:111], s[22:23], v142, s24, v[6:7]
	v_mad_u64_u32 v[112:113], s[22:23], v174, s24, v[6:7]
	v_mad_u64_u32 v[114:115], s[22:23], v144, s24, v[6:7]
	v_mad_u64_u32 v[116:117], s[22:23], v143, s24, v[6:7]
	v_mad_u64_u32 v[118:119], s[22:23], v146, s24, v[6:7]
	v_mad_u64_u32 v[120:121], s[22:23], v145, s24, v[6:7]
	v_mad_u64_u32 v[122:123], s[22:23], v148, s24, v[6:7]
	v_mad_u64_u32 v[124:125], s[22:23], v147, s24, v[6:7]
	v_mad_u64_u32 v[126:127], s[22:23], v150, s24, v[6:7]
	v_mad_u64_u32 v[128:129], s[22:23], v149, s24, v[6:7]
	v_mad_u64_u32 v[130:131], s[22:23], v152, s24, v[6:7]
	v_mad_u64_u32 v[132:133], s[22:23], v151, s24, v[6:7]
	v_mad_u64_u32 v[134:135], s[22:23], v154, s24, v[6:7]
	v_mad_u64_u32 v[136:137], s[22:23], v153, s24, v[6:7]
	v_mad_u64_u32 v[138:139], s[22:23], v156, s24, v[6:7]
	v_mad_u64_u32 v[140:141], s[22:23], v155, s24, v[6:7]
	s_waitcnt vmcnt(0)
	ds_write_b32 v110, v157
	ds_write_b32 v112, v158
	ds_write_b32 v114, v159
	ds_write_b32 v116, v160
	ds_write_b32 v118, v161
	ds_write_b32 v120, v162
	ds_write_b32 v122, v163
	ds_write_b32 v124, v164
	ds_write_b32 v126, v165
	ds_write_b32 v128, v166
	ds_write_b32 v130, v167
	ds_write_b32 v132, v168
	ds_write_b32 v134, v169
	ds_write_b32 v136, v170
	ds_write_b32 v138, v171
	ds_write_b32 v140, v172
	s_waitcnt lgkmcnt(0)
	ds_read2_b32 v[36:37], v38 offset1:33
	s_waitcnt lgkmcnt(0)
	v_cvt_pk_bf16_f32 v46, v36, v37
	ds_read2_b32 v[36:37], v38 offset0:66 offset1:99
	s_waitcnt lgkmcnt(0)
	v_cvt_pk_bf16_f32 v47, v36, v37
	ds_read2_b32 v[36:37], v38 offset0:132 offset1:165
	v_or_b32_e32 v50, v4, v7
	s_waitcnt lgkmcnt(0)
	v_cvt_pk_bf16_f32 v48, v36, v37
	ds_read2_b32 v[36:37], v38 offset0:198 offset1:231
	v_ashrrev_i32_e32 v35, 31, v34
	v_ashrrev_i32_e32 v51, 31, v50
	v_lshl_add_u64 v[52:53], v[34:35], 1, v[18:19]
	s_waitcnt lgkmcnt(0)
	v_cvt_pk_bf16_f32 v49, v36, v37
	v_lshlrev_b64 v[36:37], 11, v[50:51]
	v_lshl_add_u64 v[36:37], v[52:53], 0, v[36:37]
	global_store_dwordx4 v[36:37], v[46:49], off
	ds_read2_b32 v[34:35], v38 offset0:8 offset1:41
	s_waitcnt lgkmcnt(0)
	v_cvt_pk_bf16_f32 v34, v34, v35
	ds_read2_b32 v[36:37], v38 offset0:74 offset1:107
	v_or_b32_e32 v48, v4, v39
	v_ashrrev_i32_e32 v49, 31, v48
	v_lshlrev_b64 v[48:49], 11, v[48:49]
	s_waitcnt lgkmcnt(0)
	v_cvt_pk_bf16_f32 v35, v36, v37
	ds_read2_b32 v[36:37], v38 offset0:140 offset1:173
	v_lshl_add_u64 v[48:49], v[52:53], 0, v[48:49]
	s_waitcnt lgkmcnt(0)
	v_cvt_pk_bf16_f32 v36, v36, v37
	ds_read2_b32 v[46:47], v38 offset0:206 offset1:239
	s_waitcnt lgkmcnt(0)
	v_cvt_pk_bf16_f32 v37, v46, v47
	global_store_dwordx4 v[48:49], v[34:37], off
	v_or_b32_e32 v48, v4, v40
	ds_read2_b32 v[46:47], v38 offset0:16 offset1:49
	s_waitcnt lgkmcnt(0)
	v_cvt_pk_bf16_f32 v34, v46, v47
	ds_read2_b32 v[36:37], v38 offset0:82 offset1:115
	v_ashrrev_i32_e32 v49, 31, v48
	s_waitcnt lgkmcnt(0)
	v_cvt_pk_bf16_f32 v35, v36, v37
	ds_read2_b32 v[36:37], v38 offset0:148 offset1:181
	v_lshlrev_b64 v[48:49], 11, v[48:49]
	s_waitcnt lgkmcnt(0)
	v_cvt_pk_bf16_f32 v36, v36, v37
	ds_read2_b32 v[46:47], v38 offset0:214 offset1:247
	s_waitcnt lgkmcnt(0)
	v_cvt_pk_bf16_f32 v37, v46, v47
	v_lshl_add_u64 v[48:49], v[52:53], 0, v[48:49]
	ds_read2_b32 v[46:47], v38 offset0:24 offset1:57
	global_store_dwordx4 v[48:49], v[34:37], off
	v_or_b32_e32 v48, v4, v41
	v_ashrrev_i32_e32 v49, 31, v48
	s_waitcnt lgkmcnt(0)
	v_cvt_pk_bf16_f32 v34, v46, v47
	ds_read2_b32 v[36:37], v38 offset0:90 offset1:123
	s_waitcnt lgkmcnt(0)
	v_cvt_pk_bf16_f32 v35, v36, v37
	ds_read2_b32 v[36:37], v38 offset0:156 offset1:189
	s_waitcnt lgkmcnt(0)
	v_cvt_pk_bf16_f32 v36, v36, v37
	ds_read2_b32 v[46:47], v38 offset0:222 offset1:255
	v_lshlrev_b64 v[48:49], 11, v[48:49]
	s_waitcnt lgkmcnt(0)
	v_cvt_pk_bf16_f32 v37, v46, v47
	v_lshl_add_u64 v[46:47], v[52:53], 0, v[48:49]
	global_store_dwordx4 v[46:47], v[34:37], off
	s_waitcnt lgkmcnt(0)
	s_branch .LBB0_29
